# SwiGLU epilogue emitted 4 elements at a time; odd-mixer attention: running max over raw scores, scaled once
# speedup vs baseline: 1.0762x; 1.0054x over previous
.LBB0_56:
	ds_read_b128 v[188:191], v160
	ds_read_b128 v[192:195], v160 offset:32
	ds_read_b128 v[196:199], v161 offset:36864
	ds_read_b128 v[200:203], v161 offset:36896
	ds_read_b128 v[204:207], v160 offset:4608
	ds_read_b128 v[208:211], v160 offset:4640
	ds_read_b128 v[212:215], v161 offset:41472
	ds_read_b128 v[216:219], v161 offset:41504
	s_add_i32 s42, s43, 2
	s_waitcnt lgkmcnt(5)
	v_mfma_f32_32x32x16_bf16 v[50:65], v[188:191], v[196:199], v[50:65]
	s_waitcnt vmcnt(15)
	ds_write_b128 v184, v[66:69] offset:18432
	s_cmp_lt_u32 s42, 13
	s_cselect_b64 s[46:47], -1, 0
	s_and_b64 s[20:21], s[46:47], exec
	s_cselect_b32 s20, 0, 0x1fffff0
	s_add_i32 s20, s20, s43
	s_lshl_b32 s45, s20, 7
	s_waitcnt lgkmcnt(2)
	v_mfma_f32_32x32x16_bf16 v[34:49], v[188:191], v[212:215], v[34:49]
	s_waitcnt vmcnt(14)
	ds_write_b128 v184, v[74:77] offset:55296
	s_add_i32 s50, s45, 0x280
	s_and_b64 s[20:21], s[46:47], exec
	s_cselect_b32 s21, s31, s38
	s_cselect_b32 s20, s40, s37
	s_and_b32 s21, s21, 0xffff
	s_and_b64 s[46:47], s[46:47], exec
	s_waitcnt lgkmcnt(5)
	v_mfma_f32_32x32x16_bf16 v[16:31], v[204:207], v[196:199], v[16:31]
	s_waitcnt vmcnt(13)
	ds_write_b128 v185, v[70:73] offset:18432
	s_cselect_b32 s46, s36, s41
	s_cselect_b32 s52, s44, s39
	s_and_b32 s53, s46, 0xffff
	s_mov_b32 s54, s22
	s_mov_b32 s55, s23
	s_add_i32 s46, s45, 0x10280
	s_waitcnt lgkmcnt(4)
	v_mfma_f32_32x32x16_bf16 v[0:15], v[204:207], v[212:215], v[0:15]
	s_waitcnt vmcnt(12)
	ds_write_b128 v185, v[82:85] offset:55296
	s_waitcnt lgkmcnt(8)
	v_mfma_f32_32x32x16_bf16 v[50:65], v[192:195], v[200:203], v[50:65]
	ds_read_b128 v[220:223], v160 offset:64
	ds_read_b128 v[142:145], v160 offset:96
	s_waitcnt vmcnt(11)
	ds_write_b128 v186, v[78:81] offset:18432
	s_waitcnt lgkmcnt(7)
	v_mfma_f32_32x32x16_bf16 v[34:49], v[192:195], v[216:219], v[34:49]
	ds_read_b128 v[154:157], v161 offset:36928
	ds_read_b128 v[138:141], v161 offset:36960
	s_waitcnt vmcnt(10)
	ds_write_b128 v186, v[90:93] offset:55296
	s_waitcnt lgkmcnt(12)
	v_mfma_f32_32x32x16_bf16 v[16:31], v[208:211], v[200:203], v[16:31]
	ds_read_b128 v[146:149], v160 offset:4672
	ds_read_b128 v[130:133], v160 offset:4704
	s_waitcnt vmcnt(9)
	ds_write_b128 v187, v[86:89] offset:18432
	s_waitcnt lgkmcnt(13)
	v_mfma_f32_32x32x16_bf16 v[0:15], v[208:211], v[216:219], v[0:15]
	ds_read_b128 v[150:153], v161 offset:41536
	ds_read_b128 v[134:137], v161 offset:41568
	s_waitcnt vmcnt(8)
	ds_write_b128 v187, v[94:97] offset:55296
	s_waitcnt lgkmcnt(8)
	v_mfma_f32_32x32x16_bf16 v[50:65], v[220:223], v[154:157], v[50:65]
	buffer_load_dwordx4 v[66:69], v32, s[20:23], s50 offen
	s_waitcnt lgkmcnt(2)
	v_mfma_f32_32x32x16_bf16 v[34:49], v[220:223], v[150:153], v[34:49]
	buffer_load_dwordx4 v[74:77], v32, s[52:55], s50 offen
	s_waitcnt lgkmcnt(5)
	v_mfma_f32_32x32x16_bf16 v[16:31], v[146:149], v[154:157], v[16:31]
	buffer_load_dwordx4 v[70:73], v32, s[20:23], s46 offen
	s_waitcnt lgkmcnt(2)
	v_mfma_f32_32x32x16_bf16 v[0:15], v[146:149], v[150:153], v[0:15]
	buffer_load_dwordx4 v[82:85], v32, s[52:55], s46 offen
	s_add_i32 s46, s45, 0x20280
	s_add_i32 s45, s45, 0x30280
	s_waitcnt lgkmcnt(7)
	v_mfma_f32_32x32x16_bf16 v[50:65], v[142:145], v[138:141], v[50:65]
	buffer_load_dwordx4 v[78:81], v32, s[20:23], s46 offen
	s_waitcnt lgkmcnt(1)
	v_mfma_f32_32x32x16_bf16 v[34:49], v[142:145], v[134:137], v[34:49]
	buffer_load_dwordx4 v[90:93], v32, s[52:55], s46 offen
	s_waitcnt lgkmcnt(4)
	v_mfma_f32_32x32x16_bf16 v[16:31], v[130:133], v[138:141], v[16:31]
	buffer_load_dwordx4 v[86:89], v32, s[20:23], s45 offen
	s_waitcnt lgkmcnt(1)
	v_mfma_f32_32x32x16_bf16 v[0:15], v[130:133], v[134:137], v[0:15]
	buffer_load_dwordx4 v[94:97], v32, s[52:55], s45 offen
	s_waitcnt lgkmcnt(0)
	s_barrier
	ds_read_b128 v[188:191], v160 offset:18432
	ds_read_b128 v[192:195], v160 offset:18464
	ds_read_b128 v[196:199], v161 offset:55296
	ds_read_b128 v[200:203], v161 offset:55328
	ds_read_b128 v[204:207], v160 offset:23040
	ds_read_b128 v[208:211], v160 offset:23072
	ds_read_b128 v[212:215], v161 offset:59904
	ds_read_b128 v[216:219], v161 offset:59936
	s_waitcnt lgkmcnt(5)
	v_mfma_f32_32x32x16_bf16 v[50:65], v[188:191], v[196:199], v[50:65]
	s_waitcnt vmcnt(15)
	ds_write_b128 v184, v[98:101]
	s_cmp_lt_u32 s42, 12
	s_cselect_b64 s[46:47], -1, 0
	s_and_b64 s[20:21], s[46:47], exec
	s_cselect_b32 s20, 0, 0x1fffff0
	s_add_i32 s20, s20, s43
	s_lshl_b32 s43, s20, 7
	s_waitcnt lgkmcnt(2)
	v_mfma_f32_32x32x16_bf16 v[34:49], v[188:191], v[212:215], v[34:49]
	s_waitcnt vmcnt(14)
	ds_write_b128 v184, v[106:109] offset:36864
	s_add_i32 s45, s43, 0x300
	s_and_b64 s[20:21], s[46:47], exec
	s_cselect_b32 s21, s31, s38
	s_cselect_b32 s20, s40, s37
	s_and_b32 s21, s21, 0xffff
	s_and_b64 s[46:47], s[46:47], exec
	s_waitcnt lgkmcnt(5)
	v_mfma_f32_32x32x16_bf16 v[16:31], v[204:207], v[196:199], v[16:31]
	s_waitcnt vmcnt(13)
	ds_write_b128 v185, v[102:105]
	s_cselect_b32 s46, s36, s41
	s_cselect_b32 s52, s44, s39
	s_and_b32 s53, s46, 0xffff
	s_waitcnt lgkmcnt(4)
	v_mfma_f32_32x32x16_bf16 v[0:15], v[204:207], v[212:215], v[0:15]
	s_waitcnt vmcnt(12)
	ds_write_b128 v185, v[114:117] offset:36864
	s_waitcnt lgkmcnt(8)
	v_mfma_f32_32x32x16_bf16 v[50:65], v[192:195], v[200:203], v[50:65]
	ds_read_b128 v[220:223], v160 offset:18496
	ds_read_b128 v[142:145], v160 offset:18528
	s_waitcnt vmcnt(11)
	ds_write_b128 v186, v[110:113]
	s_waitcnt lgkmcnt(7)
	v_mfma_f32_32x32x16_bf16 v[34:49], v[192:195], v[216:219], v[34:49]
	ds_read_b128 v[154:157], v161 offset:55360
	ds_read_b128 v[138:141], v161 offset:55392
	s_waitcnt vmcnt(10)
	ds_write_b128 v186, v[122:125] offset:36864
	s_waitcnt lgkmcnt(12)
	v_mfma_f32_32x32x16_bf16 v[16:31], v[208:211], v[200:203], v[16:31]
	ds_read_b128 v[146:149], v160 offset:23104
	ds_read_b128 v[130:133], v160 offset:23136
	s_waitcnt vmcnt(9)
	ds_write_b128 v187, v[118:121]
	s_waitcnt lgkmcnt(13)
	v_mfma_f32_32x32x16_bf16 v[0:15], v[208:211], v[216:219], v[0:15]
	ds_read_b128 v[150:153], v161 offset:59968
	ds_read_b128 v[134:137], v161 offset:60000
	s_waitcnt vmcnt(8)
	ds_write_b128 v187, v[126:129] offset:36864
	s_waitcnt lgkmcnt(8)
	v_mfma_f32_32x32x16_bf16 v[50:65], v[220:223], v[154:157], v[50:65]
	buffer_load_dwordx4 v[98:101], v32, s[20:23], s45 offen
	s_waitcnt lgkmcnt(2)
	v_mfma_f32_32x32x16_bf16 v[34:49], v[220:223], v[150:153], v[34:49]
	buffer_load_dwordx4 v[106:109], v32, s[52:55], s45 offen
	s_add_i32 s45, s43, 0x10300
	s_waitcnt lgkmcnt(5)
	v_mfma_f32_32x32x16_bf16 v[16:31], v[146:149], v[154:157], v[16:31]
	buffer_load_dwordx4 v[102:105], v32, s[20:23], s45 offen
	s_waitcnt lgkmcnt(2)
	v_mfma_f32_32x32x16_bf16 v[0:15], v[146:149], v[150:153], v[0:15]
	buffer_load_dwordx4 v[114:117], v32, s[52:55], s45 offen
	s_add_i32 s45, s43, 0x20300
	s_add_i32 s43, s43, 0x30300
	s_waitcnt lgkmcnt(7)
	v_mfma_f32_32x32x16_bf16 v[50:65], v[142:145], v[138:141], v[50:65]
	buffer_load_dwordx4 v[110:113], v32, s[20:23], s45 offen
	s_waitcnt lgkmcnt(1)
	v_mfma_f32_32x32x16_bf16 v[34:49], v[142:145], v[134:137], v[34:49]
	buffer_load_dwordx4 v[122:125], v32, s[52:55], s45 offen
	s_waitcnt lgkmcnt(4)
	v_mfma_f32_32x32x16_bf16 v[16:31], v[130:133], v[138:141], v[16:31]
	buffer_load_dwordx4 v[118:121], v32, s[20:23], s43 offen
	s_waitcnt lgkmcnt(1)
	v_mfma_f32_32x32x16_bf16 v[0:15], v[130:133], v[134:137], v[0:15]
	buffer_load_dwordx4 v[126:129], v32, s[52:55], s43 offen
	s_cmp_gt_u32 s42, 13
	s_mov_b32 s43, s42
	s_waitcnt lgkmcnt(0)
	s_barrier
	s_cbranch_scc0 .LBB0_56
	v_add_u32_e32 v32, s28, v183
	s_lshl_b32 s20, s30, 6
	v_lshlrev_b32_e32 v130, 5, v181
	v_lshl_or_b32 v32, v182, 2, v32
	v_mul_lo_u32 v32, v32, s97
	v_or3_b32 v130, v130, s20, v180
	v_add_lshl_u32 v32, v130, v32, 1
	v_readlane_b32 s20, v235, 34
	v_readlane_b32 s21, v235, 35
	v_readlane_b32 s52, v233, 61
	v_readlane_b32 s62, v232, 7
	v_readlane_b32 s63, v232, 8
	s_and_b64 vcc, exec, s[0:1]
	s_mov_b32 s37, s29
	v_readlane_b32 s53, v233, 62
	v_readlane_b32 s56, v232, 1
	v_readlane_b32 s57, v232, 2
	v_readlane_b32 s58, v232, 3
	v_readlane_b32 s59, v232, 4
	v_readlane_b32 s60, v232, 5
	v_readlane_b32 s61, v232, 6
	v_readlane_b32 s64, v232, 9
	v_readlane_b32 s65, v232, 10
	v_readlane_b32 s66, v232, 11
	v_readlane_b32 s67, v232, 12
	v_readlane_b32 s63, v235, 21
	v_readlane_b32 s62, v232, 31
	v_readlane_b32 s54, v233, 63
	v_readlane_b32 s55, v232, 0
	v_mul_f32_e32 v188, 0xbfb8aa3b, v50
	v_mul_f32_e32 v189, 0xbfb8aa3b, v51
	v_mul_f32_e32 v190, 0xbfb8aa3b, v52
	v_mul_f32_e32 v191, 0xbfb8aa3b, v53
	v_exp_f32_e32 v188, v188
	v_exp_f32_e32 v189, v189
	v_exp_f32_e32 v190, v190
	v_exp_f32_e32 v191, v191
	v_mov_b32_e32 v200, v32
	v_add_u32_e32 v201, 0x1600, v32
	v_add_u32_e32 v202, 0x2c00, v32
	v_add_u32_e32 v203, 0x4200, v32
	v_add_f32_e32 v188, 1.0, v188
	v_add_f32_e32 v189, 1.0, v189
	v_add_f32_e32 v190, 1.0, v190
	v_add_f32_e32 v191, 1.0, v191
	v_rcp_f32_e32 v188, v188
	v_rcp_f32_e32 v189, v189
	v_rcp_f32_e32 v190, v190
	v_rcp_f32_e32 v191, v191
	v_mul_f32_e32 v188, v50, v188
	v_mul_f32_e32 v189, v51, v189
	v_mul_f32_e32 v190, v52, v190
	v_mul_f32_e32 v191, v53, v191
	v_mul_f32_e32 v188, v34, v188
	v_mul_f32_e32 v189, v35, v189
	v_mul_f32_e32 v190, v36, v190
	v_mul_f32_e32 v191, v37, v191
	v_cvt_pk_bf16_f32 v188, v188, s0
	v_cvt_pk_bf16_f32 v189, v189, s0
	v_cvt_pk_bf16_f32 v190, v190, s0
	v_cvt_pk_bf16_f32 v191, v191, s0
	global_store_short v200, v188, s[20:21]
	global_store_short v201, v189, s[20:21]
	global_store_short v202, v190, s[20:21]
	global_store_short v203, v191, s[20:21]
	v_mul_f32_e32 v188, 0xbfb8aa3b, v54
	v_mul_f32_e32 v189, 0xbfb8aa3b, v55
	v_mul_f32_e32 v190, 0xbfb8aa3b, v56
	v_mul_f32_e32 v191, 0xbfb8aa3b, v57
	v_exp_f32_e32 v188, v188
	v_exp_f32_e32 v189, v189
	v_exp_f32_e32 v190, v190
	v_exp_f32_e32 v191, v191
	v_add_u32_e32 v200, 0xb000, v32
	v_add_u32_e32 v201, 0xc600, v32
	v_add_u32_e32 v202, 0xdc00, v32
	v_add_u32_e32 v203, 0xf200, v32
	v_add_f32_e32 v188, 1.0, v188
	v_add_f32_e32 v189, 1.0, v189
	v_add_f32_e32 v190, 1.0, v190
	v_add_f32_e32 v191, 1.0, v191
	v_rcp_f32_e32 v188, v188
	v_rcp_f32_e32 v189, v189
	v_rcp_f32_e32 v190, v190
	v_rcp_f32_e32 v191, v191
	v_mul_f32_e32 v188, v54, v188
	v_mul_f32_e32 v189, v55, v189
	v_mul_f32_e32 v190, v56, v190
	v_mul_f32_e32 v191, v57, v191
	v_mul_f32_e32 v188, v38, v188
	v_mul_f32_e32 v189, v39, v189
	v_mul_f32_e32 v190, v40, v190
	v_mul_f32_e32 v191, v41, v191
	v_cvt_pk_bf16_f32 v188, v188, s0
	v_cvt_pk_bf16_f32 v189, v189, s0
	v_cvt_pk_bf16_f32 v190, v190, s0
	v_cvt_pk_bf16_f32 v191, v191, s0
	global_store_short v200, v188, s[20:21]
	global_store_short v201, v189, s[20:21]
	global_store_short v202, v190, s[20:21]
	global_store_short v203, v191, s[20:21]
	v_mul_f32_e32 v188, 0xbfb8aa3b, v58
	v_mul_f32_e32 v189, 0xbfb8aa3b, v59
	v_mul_f32_e32 v190, 0xbfb8aa3b, v60
	v_mul_f32_e32 v191, 0xbfb8aa3b, v61
	v_exp_f32_e32 v188, v188
	v_exp_f32_e32 v189, v189
	v_exp_f32_e32 v190, v190
	v_exp_f32_e32 v191, v191
	v_add_u32_e32 v200, 0x16000, v32
	v_add_u32_e32 v201, 0x17600, v32
	v_add_u32_e32 v202, 0x18c00, v32
	v_add_u32_e32 v203, 0x1a200, v32
	v_add_f32_e32 v188, 1.0, v188
	v_add_f32_e32 v189, 1.0, v189
	v_add_f32_e32 v190, 1.0, v190
	v_add_f32_e32 v191, 1.0, v191
	v_rcp_f32_e32 v188, v188
	v_rcp_f32_e32 v189, v189
	v_rcp_f32_e32 v190, v190
	v_rcp_f32_e32 v191, v191
	v_mul_f32_e32 v188, v58, v188
	v_mul_f32_e32 v189, v59, v189
	v_mul_f32_e32 v190, v60, v190
	v_mul_f32_e32 v191, v61, v191
	v_mul_f32_e32 v188, v42, v188
	v_mul_f32_e32 v189, v43, v189
	v_mul_f32_e32 v190, v44, v190
	v_mul_f32_e32 v191, v45, v191
	v_cvt_pk_bf16_f32 v188, v188, s0
	v_cvt_pk_bf16_f32 v189, v189, s0
	v_cvt_pk_bf16_f32 v190, v190, s0
	v_cvt_pk_bf16_f32 v191, v191, s0
	global_store_short v200, v188, s[20:21]
	global_store_short v201, v189, s[20:21]
	global_store_short v202, v190, s[20:21]
	global_store_short v203, v191, s[20:21]
	v_mul_f32_e32 v188, 0xbfb8aa3b, v62
	v_mul_f32_e32 v189, 0xbfb8aa3b, v63
	v_mul_f32_e32 v190, 0xbfb8aa3b, v64
	v_mul_f32_e32 v191, 0xbfb8aa3b, v65
	v_exp_f32_e32 v188, v188
	v_exp_f32_e32 v189, v189
	v_exp_f32_e32 v190, v190
	v_exp_f32_e32 v191, v191
	v_add_u32_e32 v200, 0x21000, v32
	v_add_u32_e32 v201, 0x22600, v32
	v_add_u32_e32 v202, 0x23c00, v32
	v_add_u32_e32 v203, 0x25200, v32
	v_add_f32_e32 v188, 1.0, v188
	v_add_f32_e32 v189, 1.0, v189
	v_add_f32_e32 v190, 1.0, v190
	v_add_f32_e32 v191, 1.0, v191
	v_rcp_f32_e32 v188, v188
	v_rcp_f32_e32 v189, v189
	v_rcp_f32_e32 v190, v190
	v_rcp_f32_e32 v191, v191
	v_mul_f32_e32 v188, v62, v188
	v_mul_f32_e32 v189, v63, v189
	v_mul_f32_e32 v190, v64, v190
	v_mul_f32_e32 v191, v65, v191
	v_mul_f32_e32 v188, v46, v188
	v_mul_f32_e32 v189, v47, v189
	v_mul_f32_e32 v190, v48, v190
	v_mul_f32_e32 v191, v49, v191
	v_cvt_pk_bf16_f32 v188, v188, s0
	v_cvt_pk_bf16_f32 v189, v189, s0
	v_cvt_pk_bf16_f32 v190, v190, s0
	v_cvt_pk_bf16_f32 v191, v191, s0
	global_store_short v200, v188, s[20:21]
	global_store_short v201, v189, s[20:21]
	global_store_short v202, v190, s[20:21]
	global_store_short v203, v191, s[20:21]
	v_mul_f32_e32 v188, 0xbfb8aa3b, v16
	v_mul_f32_e32 v189, 0xbfb8aa3b, v17
	v_mul_f32_e32 v190, 0xbfb8aa3b, v18
	v_mul_f32_e32 v191, 0xbfb8aa3b, v19
	v_exp_f32_e32 v188, v188
	v_exp_f32_e32 v189, v189
	v_exp_f32_e32 v190, v190
	v_exp_f32_e32 v191, v191
	v_add_u32_e32 v200, 0x2c000, v32
	v_add_u32_e32 v201, 0x2d600, v32
	v_add_u32_e32 v202, 0x2ec00, v32
	v_add_u32_e32 v203, 0x30200, v32
	v_add_f32_e32 v188, 1.0, v188
	v_add_f32_e32 v189, 1.0, v189
	v_add_f32_e32 v190, 1.0, v190
	v_add_f32_e32 v191, 1.0, v191
	v_rcp_f32_e32 v188, v188
	v_rcp_f32_e32 v189, v189
	v_rcp_f32_e32 v190, v190
	v_rcp_f32_e32 v191, v191
	v_mul_f32_e32 v188, v16, v188
	v_mul_f32_e32 v189, v17, v189
	v_mul_f32_e32 v190, v18, v190
	v_mul_f32_e32 v191, v19, v191
	v_mul_f32_e32 v188, v0, v188
	v_mul_f32_e32 v189, v1, v189
	v_mul_f32_e32 v190, v2, v190
	v_mul_f32_e32 v191, v3, v191
	v_cvt_pk_bf16_f32 v188, v188, s0
	v_cvt_pk_bf16_f32 v189, v189, s0
	v_cvt_pk_bf16_f32 v190, v190, s0
	v_cvt_pk_bf16_f32 v191, v191, s0
	global_store_short v200, v188, s[20:21]
	global_store_short v201, v189, s[20:21]
	global_store_short v202, v190, s[20:21]
	global_store_short v203, v191, s[20:21]
	v_mul_f32_e32 v188, 0xbfb8aa3b, v20
	v_mul_f32_e32 v189, 0xbfb8aa3b, v21
	v_mul_f32_e32 v190, 0xbfb8aa3b, v22
	v_mul_f32_e32 v191, 0xbfb8aa3b, v23
	v_exp_f32_e32 v188, v188
	v_exp_f32_e32 v189, v189
	v_exp_f32_e32 v190, v190
	v_exp_f32_e32 v191, v191
	v_add_u32_e32 v200, 0x37000, v32
	v_add_u32_e32 v201, 0x38600, v32
	v_add_u32_e32 v202, 0x39c00, v32
	v_add_u32_e32 v203, 0x3b200, v32
	v_add_f32_e32 v188, 1.0, v188
	v_add_f32_e32 v189, 1.0, v189
	v_add_f32_e32 v190, 1.0, v190
	v_add_f32_e32 v191, 1.0, v191
	v_rcp_f32_e32 v188, v188
	v_rcp_f32_e32 v189, v189
	v_rcp_f32_e32 v190, v190
	v_rcp_f32_e32 v191, v191
	v_mul_f32_e32 v188, v20, v188
	v_mul_f32_e32 v189, v21, v189
	v_mul_f32_e32 v190, v22, v190
	v_mul_f32_e32 v191, v23, v191
	v_mul_f32_e32 v188, v4, v188
	v_mul_f32_e32 v189, v5, v189
	v_mul_f32_e32 v190, v6, v190
	v_mul_f32_e32 v191, v7, v191
	v_cvt_pk_bf16_f32 v188, v188, s0
	v_cvt_pk_bf16_f32 v189, v189, s0
	v_cvt_pk_bf16_f32 v190, v190, s0
	v_cvt_pk_bf16_f32 v191, v191, s0
	global_store_short v200, v188, s[20:21]
	global_store_short v201, v189, s[20:21]
	global_store_short v202, v190, s[20:21]
	global_store_short v203, v191, s[20:21]
	v_mul_f32_e32 v188, 0xbfb8aa3b, v24
	v_mul_f32_e32 v189, 0xbfb8aa3b, v25
	v_mul_f32_e32 v190, 0xbfb8aa3b, v26
	v_mul_f32_e32 v191, 0xbfb8aa3b, v27
	v_exp_f32_e32 v188, v188
	v_exp_f32_e32 v189, v189
	v_exp_f32_e32 v190, v190
	v_exp_f32_e32 v191, v191
	v_add_u32_e32 v200, 0x42000, v32
	v_add_u32_e32 v201, 0x43600, v32
	v_add_u32_e32 v202, 0x44c00, v32
	v_add_u32_e32 v203, 0x46200, v32
	v_add_f32_e32 v188, 1.0, v188
	v_add_f32_e32 v189, 1.0, v189
	v_add_f32_e32 v190, 1.0, v190
	v_add_f32_e32 v191, 1.0, v191
	v_rcp_f32_e32 v188, v188
	v_rcp_f32_e32 v189, v189
	v_rcp_f32_e32 v190, v190
	v_rcp_f32_e32 v191, v191
	v_mul_f32_e32 v188, v24, v188
	v_mul_f32_e32 v189, v25, v189
	v_mul_f32_e32 v190, v26, v190
	v_mul_f32_e32 v191, v27, v191
	v_mul_f32_e32 v188, v8, v188
	v_mul_f32_e32 v189, v9, v189
	v_mul_f32_e32 v190, v10, v190
	v_mul_f32_e32 v191, v11, v191
	v_cvt_pk_bf16_f32 v188, v188, s0
	v_cvt_pk_bf16_f32 v189, v189, s0
	v_cvt_pk_bf16_f32 v190, v190, s0
	v_cvt_pk_bf16_f32 v191, v191, s0
	global_store_short v200, v188, s[20:21]
	global_store_short v201, v189, s[20:21]
	global_store_short v202, v190, s[20:21]
	global_store_short v203, v191, s[20:21]
	v_mul_f32_e32 v188, 0xbfb8aa3b, v28
	v_mul_f32_e32 v189, 0xbfb8aa3b, v29
	v_mul_f32_e32 v190, 0xbfb8aa3b, v30
	v_mul_f32_e32 v191, 0xbfb8aa3b, v31
	v_exp_f32_e32 v188, v188
	v_exp_f32_e32 v189, v189
	v_exp_f32_e32 v190, v190
	v_exp_f32_e32 v191, v191
	v_add_u32_e32 v200, 0x4d000, v32
	v_add_u32_e32 v201, 0x4e600, v32
	v_add_u32_e32 v202, 0x4fc00, v32
	v_add_u32_e32 v203, 0x51200, v32
	v_add_f32_e32 v188, 1.0, v188
	v_add_f32_e32 v189, 1.0, v189
	v_add_f32_e32 v190, 1.0, v190
	v_add_f32_e32 v191, 1.0, v191
	v_rcp_f32_e32 v188, v188
	v_rcp_f32_e32 v189, v189
	v_rcp_f32_e32 v190, v190
	v_rcp_f32_e32 v191, v191
	v_mul_f32_e32 v188, v28, v188
	v_mul_f32_e32 v189, v29, v189
	v_mul_f32_e32 v190, v30, v190
	v_mul_f32_e32 v191, v31, v191
	v_mul_f32_e32 v188, v12, v188
	v_mul_f32_e32 v189, v13, v189
	v_mul_f32_e32 v190, v14, v190
	v_mul_f32_e32 v191, v15, v191
	v_cvt_pk_bf16_f32 v188, v188, s0
	v_cvt_pk_bf16_f32 v189, v189, s0
	v_cvt_pk_bf16_f32 v190, v190, s0
	v_cvt_pk_bf16_f32 v191, v191, s0
	global_store_short v200, v188, s[20:21]
	global_store_short v201, v189, s[20:21]
	global_store_short v202, v190, s[20:21]
	global_store_short v203, v191, s[20:21]
	s_mov_b64 s[20:21], 0
	s_cbranch_vccz .LBB0_51

.LBB0_177:
	s_bitcmp1_b32 s47, 0
	s_cselect_b32 s52, 0x4800, 0
	s_add_i32 s46, s47, 1
	s_cmp_lt_u32 s46, s44
	s_cselect_b32 s47, s46, s47
	s_cmp_lt_u32 s47, s25
	s_cselect_b64 s[48:49], -1, 0
	s_and_b64 s[50:51], s[48:49], exec
	s_cselect_b32 s51, s41, s43
	s_cselect_b32 s50, s40, s42
	s_sub_i32 s53, s47, s25
	s_min_u32 s47, s47, s53
	s_lshl_b32 s47, s47, 6
	s_and_b64 s[48:49], s[48:49], exec
	v_or_b32_e32 v34, s52, v32
	v_add_u32_e32 v38, s47, v98
	v_add_u32_e32 v40, s47, v100
	s_cselect_b32 s48, 0, 0x400
	v_lshl_add_u32 v36, v109, 1, v34
	v_ashrrev_i32_e32 v39, 31, v38
	v_ashrrev_i32_e32 v41, 31, v40
	s_add_i32 s48, s47, s48
	v_lshl_add_u32 v34, v112, 1, v34
	s_waitcnt vmcnt(0)
	ds_write_b128 v36, v[90:93]
	ds_write_b128 v36, v[94:97] offset:9216
	ds_write_b128 v34, v[86:89]
	ds_write_b128 v34, v[82:85] offset:9216
	v_lshl_add_u64 v[36:37], s[50:51], 0, v[32:33]
	v_lshlrev_b64 v[38:39], 9, v[38:39]
	v_lshlrev_b64 v[40:41], 9, v[40:41]
	s_ashr_i32 s49, s48, 31
	v_lshl_add_u64 v[38:39], v[36:37], 0, v[38:39]
	v_lshl_add_u64 v[36:37], v[36:37], 0, v[40:41]
	v_lshl_add_u64 v[40:41], s[48:49], 1, v[102:103]
	s_waitcnt lgkmcnt(0)
	s_barrier
	global_load_dwordx4 v[90:93], v[38:39], off
	global_load_dwordx4 v[86:89], v[36:37], off
	v_lshl_add_u64 v[36:37], v[106:107], 1, v[40:41]
	v_lshl_add_u64 v[38:39], v[104:105], 1, v[40:41]
	global_load_dwordx4 v[94:97], v[36:37], off
	global_load_dwordx4 v[82:85], v[38:39], off
	v_mov_b32_e32 v115, v35
	s_setprio 1
	v_lshlrev_b32_e32 v34, 1, v99
	v_add3_u32 v126, s52, v101, v34
	ds_read_b128 v[34:37], v126
	ds_read_b128 v[116:119], v126 offset:32
	ds_read_b128 v[50:53], v126 offset:4608
	s_waitcnt lgkmcnt(2)
	v_mfma_f32_32x32x16_bf16 v[34:49], v[34:37], v[66:69], 0
	s_waitcnt lgkmcnt(1)
	v_mfma_f32_32x32x16_bf16 v[34:49], v[116:119], v[70:73], v[34:49]
	ds_read_b128 v[116:119], v126 offset:4640
	s_waitcnt lgkmcnt(1)
	v_mfma_f32_32x32x16_bf16 v[50:65], v[50:53], v[66:69], 0
	s_waitcnt lgkmcnt(0)
	v_mfma_f32_32x32x16_bf16 v[50:65], v[116:119], v[70:73], v[50:65]
	ds_read_b128 v[116:119], v126 offset:64
	s_waitcnt lgkmcnt(0)
	v_mfma_f32_32x32x16_bf16 v[34:49], v[116:119], v[74:77], v[34:49]
	ds_read_b128 v[116:119], v126 offset:4672
	s_waitcnt lgkmcnt(0)
	v_mfma_f32_32x32x16_bf16 v[50:65], v[116:119], v[74:77], v[50:65]
	ds_read_b128 v[116:119], v126 offset:96
	s_waitcnt lgkmcnt(0)
	v_mfma_f32_32x32x16_bf16 v[34:49], v[116:119], v[78:81], v[34:49]
	ds_read_b128 v[116:119], v126 offset:4704
	s_waitcnt lgkmcnt(0)
	v_mfma_f32_32x32x16_bf16 v[50:65], v[116:119], v[78:81], v[50:65]
	s_setprio 0
	s_nop 7
	s_nop 2
	v_max3_f32 v116, v34, v50, v35
	v_max3_f32 v117, v51, v36, v52
	v_max3_f32 v116, v116, v37, v53
	v_max3_f32 v117, v117, v38, v54
	v_max3_f32 v116, v116, v39, v55
	v_max3_f32 v117, v117, v40, v56
	v_max3_f32 v116, v116, v41, v57
	v_max3_f32 v117, v117, v42, v58
	v_max3_f32 v116, v116, v43, v59
	v_max3_f32 v117, v117, v44, v60
	v_max3_f32 v116, v116, v45, v61
	v_max3_f32 v117, v117, v46, v62
	v_max3_f32 v116, v116, v47, v63
	v_max3_f32 v117, v117, v48, v64
	v_max3_f32 v116, v116, v49, v65
	v_max_f32_e32 v116, v116, v117
	v_mul_f32_e32 v116, 0x3e38aa3b, v116
	v_mov_b32_e32 v117, v116
	s_nop 1
	v_permlane32_swap_b32_e32 v116, v117
	v_max_f32_e32 v117, v117, v117
	v_max_f32_e32 v116, v116, v116
	v_max_f32_e32 v116, v116, v117
	v_add_f32_e32 v117, 0x41000000, v114
	v_cmp_gt_f32_e32 vcc, v116, v117
	s_nop 1
	v_cndmask_b32_e32 v127, v114, v116, vcc
	v_fma_f32 v34, v34, s78, -v127
	v_exp_f32_e32 v128, v34
	v_fma_f32 v34, v50, s78, -v127
	v_exp_f32_e32 v129, v34
	v_fma_f32 v34, v35, s78, -v127
	v_exp_f32_e32 v116, v34
	v_fma_f32 v34, v51, s78, -v127
	v_exp_f32_e32 v34, v34
	v_add_f32_e32 v117, v128, v129
	v_mov_b32_e32 v35, v33
	v_pk_add_f32 v[50:51], v[116:117], v[34:35]
	v_fma_f32 v35, v36, s78, -v127
	v_exp_f32_e32 v117, v35
	v_fma_f32 v35, v52, s78, -v127
	v_exp_f32_e32 v130, v35
	v_fma_f32 v35, v37, s78, -v127
	v_pk_add_f32 v[50:51], v[50:51], v[50:51] op_sel_hi:[0,1]
	v_exp_f32_e32 v118, v35
	v_fma_f32 v35, v53, s78, -v127
	v_exp_f32_e32 v50, v35
	v_add_f32_e32 v119, v117, v130
	v_fma_f32 v35, v38, s78, -v127
	v_pk_add_f32 v[36:37], v[118:119], v[50:51]
	v_exp_f32_e32 v51, v35
	v_fma_f32 v35, v54, s78, -v127
	v_exp_f32_e32 v119, v35
	v_fma_f32 v35, v39, s78, -v127
	v_pk_add_f32 v[52:53], v[36:37], v[36:37] op_sel_hi:[0,1]
	v_exp_f32_e32 v120, v35
	v_fma_f32 v35, v55, s78, -v127
	v_exp_f32_e32 v52, v35
	v_add_f32_e32 v121, v51, v119
	v_fma_f32 v35, v40, s78, -v127
	v_pk_add_f32 v[36:37], v[120:121], v[52:53]
	v_exp_f32_e32 v53, v35
	v_fma_f32 v35, v56, s78, -v127
	v_exp_f32_e32 v121, v35
	v_fma_f32 v35, v41, s78, -v127
	v_pk_add_f32 v[54:55], v[36:37], v[36:37] op_sel_hi:[0,1]
	v_exp_f32_e32 v56, v35
	v_fma_f32 v35, v57, s78, -v127
	v_exp_f32_e32 v54, v35
	v_add_f32_e32 v57, v53, v121
	v_fma_f32 v35, v42, s78, -v127
	v_pk_add_f32 v[36:37], v[56:57], v[54:55]
	v_exp_f32_e32 v55, v35
	v_fma_f32 v35, v58, s78, -v127
	v_exp_f32_e32 v131, v35
	v_fma_f32 v35, v43, s78, -v127
	v_pk_add_f32 v[36:37], v[36:37], v[36:37] op_sel_hi:[0,1]
	v_exp_f32_e32 v122, v35
	v_fma_f32 v35, v59, s78, -v127
	v_exp_f32_e32 v36, v35
	v_add_f32_e32 v123, v55, v131
	v_fma_f32 v35, v44, s78, -v127
	v_pk_add_f32 v[38:39], v[122:123], v[36:37]
	v_exp_f32_e32 v37, v35
	v_fma_f32 v35, v60, s78, -v127
	v_exp_f32_e32 v123, v35
	v_fma_f32 v35, v45, s78, -v127
	v_pk_add_f32 v[38:39], v[38:39], v[38:39] op_sel_hi:[0,1]
	v_exp_f32_e32 v60, v35
	v_fma_f32 v35, v61, s78, -v127
	v_exp_f32_e32 v38, v35
	v_add_f32_e32 v61, v37, v123
	v_fma_f32 v35, v46, s78, -v127
	v_pk_add_f32 v[40:41], v[60:61], v[38:39]
	v_exp_f32_e32 v39, v35
	v_fma_f32 v35, v62, s78, -v127
	v_exp_f32_e32 v61, v35
	v_fma_f32 v35, v47, s78, -v127
	v_pk_add_f32 v[40:41], v[40:41], v[40:41] op_sel_hi:[0,1]
	v_exp_f32_e32 v62, v35
	v_fma_f32 v35, v63, s78, -v127
	v_exp_f32_e32 v40, v35
	v_add_f32_e32 v63, v39, v61
	v_fma_f32 v35, v48, s78, -v127
	v_pk_add_f32 v[42:43], v[62:63], v[40:41]
	v_exp_f32_e32 v41, v35
	v_fma_f32 v35, v64, s78, -v127
	v_exp_f32_e32 v63, v35
	v_fma_f32 v35, v49, s78, -v127
	v_pk_add_f32 v[124:125], v[42:43], v[42:43] op_sel_hi:[0,1]
	v_exp_f32_e32 v64, v35
	v_fma_f32 v35, v65, s78, -v127
	v_exp_f32_e32 v124, v35
	v_add_f32_e32 v65, v41, v63
	v_sub_f32_e32 v35, v114, v127
	v_exp_f32_e32 v44, v35
	v_pk_add_f32 v[42:43], v[64:65], v[124:125]
	v_pk_add_f32 v[42:43], v[42:43], v[42:43] op_sel:[0,1] op_sel_hi:[1,0]
	v_mov_b32_e32 v35, v42
	s_nop 1
	v_permlane32_swap_b32_e32 v42, v35
	v_add_f32_e32 v35, v42, v35
	v_fmac_f32_e32 v35, v115, v44
	v_cmp_neq_f32_e32 vcc, 1.0, v44
	s_cbranch_vccz .Lattn_norescale_d64
	v_pk_mul_f32 v[14:15], v[14:15], v[44:45] op_sel_hi:[1,0]
	v_pk_mul_f32 v[12:13], v[12:13], v[44:45] op_sel_hi:[1,0]
	v_pk_mul_f32 v[10:11], v[10:11], v[44:45] op_sel_hi:[1,0]
	v_pk_mul_f32 v[8:9], v[8:9], v[44:45] op_sel_hi:[1,0]
	v_pk_mul_f32 v[6:7], v[6:7], v[44:45] op_sel_hi:[1,0]
	v_pk_mul_f32 v[4:5], v[4:5], v[44:45] op_sel_hi:[1,0]
	v_pk_mul_f32 v[2:3], v[2:3], v[44:45] op_sel_hi:[1,0]
	v_pk_mul_f32 v[0:1], v[0:1], v[44:45] op_sel_hi:[1,0]
	v_pk_mul_f32 v[30:31], v[30:31], v[44:45] op_sel_hi:[1,0]
	v_pk_mul_f32 v[28:29], v[28:29], v[44:45] op_sel_hi:[1,0]
	v_pk_mul_f32 v[26:27], v[26:27], v[44:45] op_sel_hi:[1,0]
	v_pk_mul_f32 v[24:25], v[24:25], v[44:45] op_sel_hi:[1,0]
	v_pk_mul_f32 v[22:23], v[22:23], v[44:45] op_sel_hi:[1,0]
	v_pk_mul_f32 v[20:21], v[20:21], v[44:45] op_sel_hi:[1,0]
	v_pk_mul_f32 v[18:19], v[18:19], v[44:45] op_sel_hi:[1,0]
	v_pk_mul_f32 v[16:17], v[16:17], v[44:45] op_sel_hi:[1,0]

.LBB0_185:
	s_bitcmp1_b32 s44, 0
	s_cselect_b32 s43, 0x5800, 0
	s_add_i32 s42, s44, 1
	s_cmp_lt_u32 s42, s41
	s_cselect_b32 s48, s42, s44
	s_cmp_lt_u32 s48, s25
	s_cselect_b64 s[44:45], -1, 0
	s_and_b64 s[46:47], s[44:45], exec
	s_cselect_b32 s47, s39, s30
	s_cselect_b32 s46, s38, s28
	s_sub_i32 s49, s48, s25
	v_or_b32_e32 v34, s43, v32
	s_min_u32 s48, s48, s49
	v_add3_u32 v36, s43, v113, v126
	v_add_u32_e32 v37, v34, v119
	s_lshl_b32 s48, s48, 6
	v_add_u32_e32 v38, v34, v128
	v_add_u32_e32 v39, v34, v129
	v_add_u32_e32 v34, v34, v130
	s_waitcnt vmcnt(1)
	ds_write_b128 v37, v[102:105]
	ds_write_b128 v38, v[98:101] offset:13312
	ds_write_b128 v39, v[90:93]
	ds_write_b128 v34, v[94:97] offset:13312
	s_waitcnt vmcnt(0)
	ds_write_b128 v36, v[106:109] offset:128
	v_lshl_add_u64 v[36:37], s[46:47], 0, v[32:33]
	s_and_b64 s[46:47], s[44:45], exec
	v_add_u32_e32 v38, s48, v114
	v_add_u32_e32 v40, s48, v116
	s_cselect_b32 s46, 0, 0x400
	v_ashrrev_i32_e32 v39, 31, v38
	v_ashrrev_i32_e32 v41, 31, v40
	s_add_i32 s46, s48, s46
	v_add_u32_e32 v42, s48, v118
	v_lshlrev_b64 v[38:39], 10, v[38:39]
	v_lshlrev_b64 v[40:41], 10, v[40:41]
	s_ashr_i32 s47, s46, 31
	v_ashrrev_i32_e32 v43, 31, v42
	v_lshl_add_u64 v[38:39], v[36:37], 0, v[38:39]
	v_lshl_add_u64 v[36:37], v[36:37], 0, v[40:41]
	v_lshl_add_u64 v[40:41], s[46:47], 1, v[120:121]
	s_and_b64 s[44:45], s[44:45], exec
	s_waitcnt lgkmcnt(0)
	s_barrier
	v_lshlrev_b64 v[42:43], 6, v[42:43]
	global_load_dwordx4 v[102:105], v[38:39], off
	global_load_dwordx4 v[90:93], v[36:37], off
	v_lshl_add_u64 v[36:37], v[124:125], 1, v[40:41]
	s_cselect_b32 s45, s37, s40
	s_cselect_b32 s44, s36, s31
	v_mov_b32_e32 v127, v33
	v_lshl_add_u64 v[38:39], v[122:123], 1, v[40:41]
	global_load_dwordx4 v[98:101], v[36:37], off
	global_load_dwordx4 v[94:97], v[38:39], off
	v_lshl_add_u64 v[36:37], s[44:45], 0, v[42:43]
	v_lshl_add_u64 v[36:37], v[36:37], 0, v[126:127]
	global_load_dwordx4 v[106:109], v[36:37], off
	v_mov_b32_e32 v127, v35
	s_setprio 1
	v_add3_u32 v133, s43, v115, v131
	ds_read_b128 v[34:37], v133
	ds_read_b128 v[134:137], v133 offset:32
	ds_read_b128 v[50:53], v133 offset:6656
	s_waitcnt lgkmcnt(2)
	v_mfma_f32_32x32x16_bf16 v[34:49], v[34:37], v[66:69], 0
	s_waitcnt lgkmcnt(1)
	v_mfma_f32_32x32x16_bf16 v[34:49], v[134:137], v[70:73], v[34:49]
	ds_read_b128 v[134:137], v133 offset:6688
	s_waitcnt lgkmcnt(1)
	v_mfma_f32_32x32x16_bf16 v[50:65], v[50:53], v[66:69], 0
	s_waitcnt lgkmcnt(0)
	v_mfma_f32_32x32x16_bf16 v[50:65], v[134:137], v[70:73], v[50:65]
	ds_read_b128 v[134:137], v133 offset:64
	s_waitcnt lgkmcnt(0)
	v_mfma_f32_32x32x16_bf16 v[34:49], v[134:137], v[74:77], v[34:49]
	ds_read_b128 v[134:137], v133 offset:6720
	s_waitcnt lgkmcnt(0)
	v_mfma_f32_32x32x16_bf16 v[50:65], v[134:137], v[74:77], v[50:65]
	ds_read_b128 v[134:137], v133 offset:96
	s_waitcnt lgkmcnt(0)
	v_mfma_f32_32x32x16_bf16 v[34:49], v[134:137], v[78:81], v[34:49]
	ds_read_b128 v[134:137], v133 offset:6752
	s_waitcnt lgkmcnt(0)
	v_mfma_f32_32x32x16_bf16 v[50:65], v[134:137], v[78:81], v[50:65]
	ds_read_b128 v[134:137], v133 offset:128
	s_waitcnt lgkmcnt(0)
	v_mfma_f32_32x32x16_bf16 v[34:49], v[134:137], v[82:85], v[34:49]
	ds_read_b128 v[134:137], v133 offset:6784
	s_waitcnt lgkmcnt(0)
	v_mfma_f32_32x32x16_bf16 v[50:65], v[134:137], v[82:85], v[50:65]
	ds_read_b128 v[134:137], v133 offset:160
	s_waitcnt lgkmcnt(0)
	v_mfma_f32_32x32x16_bf16 v[34:49], v[134:137], v[86:89], v[34:49]
	ds_read_b128 v[134:137], v133 offset:6816
	s_waitcnt lgkmcnt(0)
	v_mfma_f32_32x32x16_bf16 v[50:65], v[134:137], v[86:89], v[50:65]
	s_setprio 0
	s_nop 7
	s_nop 2
	v_max3_f32 v133, v34, v50, v35
	v_max3_f32 v134, v51, v36, v52
	v_max3_f32 v133, v133, v37, v53
	v_max3_f32 v134, v134, v38, v54
	v_max3_f32 v133, v133, v39, v55
	v_max3_f32 v134, v134, v40, v56
	v_max3_f32 v133, v133, v41, v57
	v_max3_f32 v134, v134, v42, v58
	v_max3_f32 v133, v133, v43, v59
	v_max3_f32 v134, v134, v44, v60
	v_max3_f32 v133, v133, v45, v61
	v_max3_f32 v134, v134, v46, v62
	v_max3_f32 v133, v133, v47, v63
	v_max3_f32 v134, v134, v48, v64
	v_max3_f32 v133, v133, v49, v65
	v_max_f32_e32 v133, v133, v134
	v_mul_f32_e32 v133, 0x3e16c740, v133
	v_mov_b32_e32 v134, v133
	s_nop 1
	v_permlane32_swap_b32_e32 v133, v134
	v_max_f32_e32 v134, v134, v134
	v_max_f32_e32 v133, v133, v133
	v_max_f32_e32 v133, v133, v134
	v_add_f32_e32 v134, 0x41000000, v132
	v_cmp_gt_f32_e32 vcc, v133, v134
	s_nop 1
	v_cndmask_b32_e32 v133, v132, v133, vcc
	v_fma_f32 v34, v34, s73, -v133
	v_exp_f32_e32 v146, v34
	v_fma_f32 v34, v50, s73, -v133
	v_exp_f32_e32 v147, v34
	v_fma_f32 v34, v35, s73, -v133
	v_exp_f32_e32 v134, v34
	v_fma_f32 v34, v51, s73, -v133
	v_exp_f32_e32 v34, v34
	v_add_f32_e32 v135, v146, v147
	v_mov_b32_e32 v35, v33
	v_pk_add_f32 v[50:51], v[134:135], v[34:35]
	v_fma_f32 v35, v36, s73, -v133
	v_exp_f32_e32 v135, v35
	v_fma_f32 v35, v52, s73, -v133
	v_exp_f32_e32 v148, v35
	v_fma_f32 v35, v37, s73, -v133
	v_pk_add_f32 v[50:51], v[50:51], v[50:51] op_sel_hi:[0,1]
	v_exp_f32_e32 v136, v35
	v_fma_f32 v35, v53, s73, -v133
	v_exp_f32_e32 v50, v35
	v_add_f32_e32 v137, v135, v148
	v_fma_f32 v35, v38, s73, -v133
	v_pk_add_f32 v[36:37], v[136:137], v[50:51]
	v_exp_f32_e32 v51, v35
	v_fma_f32 v35, v54, s73, -v133
	v_exp_f32_e32 v137, v35
	v_fma_f32 v35, v39, s73, -v133
	v_pk_add_f32 v[52:53], v[36:37], v[36:37] op_sel_hi:[0,1]
	v_exp_f32_e32 v138, v35
	v_fma_f32 v35, v55, s73, -v133
	v_exp_f32_e32 v52, v35
	v_add_f32_e32 v139, v51, v137
	v_fma_f32 v35, v40, s73, -v133
	v_pk_add_f32 v[36:37], v[138:139], v[52:53]
	v_exp_f32_e32 v53, v35
	v_fma_f32 v35, v56, s73, -v133
	v_exp_f32_e32 v139, v35
	v_fma_f32 v35, v41, s73, -v133
	v_pk_add_f32 v[54:55], v[36:37], v[36:37] op_sel_hi:[0,1]
	v_exp_f32_e32 v56, v35
	v_fma_f32 v35, v57, s73, -v133
	v_exp_f32_e32 v54, v35
	v_add_f32_e32 v57, v53, v139
	v_fma_f32 v35, v42, s73, -v133
	v_pk_add_f32 v[36:37], v[56:57], v[54:55]
	v_exp_f32_e32 v55, v35
	v_fma_f32 v35, v58, s73, -v133
	v_exp_f32_e32 v149, v35
	v_fma_f32 v35, v43, s73, -v133
	v_pk_add_f32 v[36:37], v[36:37], v[36:37] op_sel_hi:[0,1]
	v_exp_f32_e32 v140, v35
	v_fma_f32 v35, v59, s73, -v133
	v_exp_f32_e32 v36, v35
	v_add_f32_e32 v141, v55, v149
	v_fma_f32 v35, v44, s73, -v133
	v_pk_add_f32 v[38:39], v[140:141], v[36:37]
	v_exp_f32_e32 v37, v35
	v_fma_f32 v35, v60, s73, -v133
	v_exp_f32_e32 v141, v35
	v_fma_f32 v35, v45, s73, -v133
	v_pk_add_f32 v[38:39], v[38:39], v[38:39] op_sel_hi:[0,1]
	v_exp_f32_e32 v142, v35
	v_fma_f32 v35, v61, s73, -v133
	v_exp_f32_e32 v38, v35
	v_add_f32_e32 v143, v37, v141
	v_fma_f32 v35, v46, s73, -v133
	v_pk_add_f32 v[40:41], v[142:143], v[38:39]
	v_exp_f32_e32 v39, v35
	v_fma_f32 v35, v62, s73, -v133
	v_exp_f32_e32 v143, v35
	v_fma_f32 v35, v47, s73, -v133
	v_pk_add_f32 v[40:41], v[40:41], v[40:41] op_sel_hi:[0,1]
	v_exp_f32_e32 v144, v35
	v_fma_f32 v35, v63, s73, -v133
	v_exp_f32_e32 v40, v35
	v_add_f32_e32 v145, v39, v143
	v_fma_f32 v35, v48, s73, -v133
	v_pk_add_f32 v[42:43], v[144:145], v[40:41]
	v_exp_f32_e32 v41, v35
	v_fma_f32 v35, v64, s73, -v133
	v_exp_f32_e32 v64, v35
	v_fma_f32 v35, v49, s73, -v133
	v_pk_add_f32 v[42:43], v[42:43], v[42:43] op_sel_hi:[0,1]
	v_exp_f32_e32 v48, v35
	v_fma_f32 v35, v65, s73, -v133
	v_exp_f32_e32 v42, v35
	v_add_f32_e32 v49, v41, v64
	v_sub_f32_e32 v35, v132, v133
	v_exp_f32_e32 v46, v35
	v_pk_add_f32 v[44:45], v[48:49], v[42:43]
	v_pk_add_f32 v[44:45], v[44:45], v[44:45] op_sel:[0,1] op_sel_hi:[1,0]
	v_mov_b32_e32 v35, v44
	s_nop 1
	v_permlane32_swap_b32_e32 v44, v35
	v_add_f32_e32 v35, v44, v35
	v_fmac_f32_e32 v35, v127, v46
	v_cmp_neq_f32_e32 vcc, 1.0, v46
	s_cbranch_vccz .Lattn_norescale_d96
	v_pk_mul_f32 v[14:15], v[14:15], v[46:47] op_sel_hi:[1,0]
	v_pk_mul_f32 v[12:13], v[12:13], v[46:47] op_sel_hi:[1,0]
	v_pk_mul_f32 v[10:11], v[10:11], v[46:47] op_sel_hi:[1,0]
	v_pk_mul_f32 v[8:9], v[8:9], v[46:47] op_sel_hi:[1,0]
	v_pk_mul_f32 v[6:7], v[6:7], v[46:47] op_sel_hi:[1,0]
	v_pk_mul_f32 v[4:5], v[4:5], v[46:47] op_sel_hi:[1,0]
	v_pk_mul_f32 v[2:3], v[2:3], v[46:47] op_sel_hi:[1,0]
	v_pk_mul_f32 v[0:1], v[0:1], v[46:47] op_sel_hi:[1,0]
	v_pk_mul_f32 v[30:31], v[30:31], v[46:47] op_sel_hi:[1,0]
	v_pk_mul_f32 v[28:29], v[28:29], v[46:47] op_sel_hi:[1,0]
	v_pk_mul_f32 v[26:27], v[26:27], v[46:47] op_sel_hi:[1,0]
	v_pk_mul_f32 v[24:25], v[24:25], v[46:47] op_sel_hi:[1,0]
	v_pk_mul_f32 v[22:23], v[22:23], v[46:47] op_sel_hi:[1,0]
	v_pk_mul_f32 v[20:21], v[20:21], v[46:47] op_sel_hi:[1,0]
	v_pk_mul_f32 v[18:19], v[18:19], v[46:47] op_sel_hi:[1,0]
	v_pk_mul_f32 v[16:17], v[16:17], v[46:47] op_sel_hi:[1,0]
